# seam: first look at the team's flags issued right after the own flag store (on top of the parked census/mode)
# speedup vs baseline: 1.0019x; 1.0019x over previous
.Lxb_noinv:
	s_or_b64 exec, exec, s[4:5]
	v_cmp_eq_u32_e32 vcc, 0, v210
	s_and_saveexec_b64 s[4:5], vcc
	s_cbranch_execz .LBB0_463
	v_readlane_b32 s6, v240, 5
	v_readlane_b32 s7, v240, 6
	v_readlane_b32 s8, v240, 0
	s_add_i32 s101, s101, 1
	v_mov_b32_e32 v2, s101
	s_and_b32 s9, s8, 7
	s_lshl_b32 s9, s9, 8
	s_add_u32 s9, s9, 0x12000
	s_add_u32 s12, s6, s9
	s_addc_u32 s13, s7, 0
	s_lshr_b32 s9, s8, 3
	s_lshl_b32 s9, s9, 2
	v_mov_b32_e32 v3, s9
	global_store_dword v3, v2, s[12:13]
	s_bfe_u32 s9, s8, 0x20003
	s_lshl_b32 s9, s9, 2
	s_mov_b32 exec_lo, 0xff
	s_mov_b32 exec_hi, 0
	v_mbcnt_lo_u32_b32 v5, -1, 0
	v_lshlrev_b32_e32 v5, 4, v5
	v_add_u32_e32 v5, s9, v5
	global_load_dword v6, v5, s[12:13] sc1
	s_mov_b64 exec, 1
	s_and_b32 s3, s3, 15
	s_lshl_b32 s3, s3, 8
	s_cmp_eq_u32 s101, 1
	s_cbranch_scc1 .Lxb_first
	v_readlane_b32 s10, v238, 32
	v_readlane_b32 s11, v238, 33
	v_mov_b32_e32 v2, 1
	s_lshl_b32 s9, s8, 6
	s_add_u32 s9, s9, 0x4000
	s_add_u32 s14, s6, s9
	s_addc_u32 s15, s7, 0
	v_readlane_b32 s9, v238, 34
	s_branch .Lxb_have2

.Lxb_have2:
	s_cmp_eq_u32 s9, 1
	s_cbranch_scc0 .Lxb_grid
	s_mov_b32 s9, 0x3cfdf3f4
	s_bitcmp1_b32 s9, s70
	s_cbranch_scc0 .Lxb_grid
	s_and_b32 s9, s8, 7
	s_lshl_b32 s9, s9, 8
	s_add_u32 s9, s9, 0x12000
	s_add_u32 s12, s6, s9
	s_addc_u32 s13, s7, 0
	s_lshr_b32 s9, s8, 3
	s_lshl_b32 s9, s9, 2
	s_bfe_u32 s9, s8, 0x20003
	s_lshl_b32 s9, s9, 2
	s_mov_b32 exec_lo, 0xff
	s_mov_b32 exec_hi, 0
	v_mbcnt_lo_u32_b32 v3, -1, 0
	v_lshlrev_b32_e32 v3, 4, v3
	v_add_u32_e32 v3, s9, v3
	s_mov_b32 s9, 0
	s_waitcnt vmcnt(0)
	v_cmp_gt_u32_e32 vcc, s101, v6
	s_cbranch_vccz .Lxb_ldone
